# LRU unit: redundant workgroup barrier after the output stage removed (next LDS writers are already behind another barrier)
# baseline (speedup 1.0000x reference)
.LBB0_736:
	ds_read_u16 v49, v124 offset:37440
	v_fma_f32 v44, v151, v47, v44
	v_fmac_f32_e32 v44, v52, v46
	v_fmac_f32_e32 v45, v150, v47
	v_fmac_f32_e32 v45, v54, v46
	s_waitcnt lgkmcnt(0)
	v_lshlrev_b32_e32 v49, 16, v49
	v_mul_f32_e32 v44, v44, v49
	v_cvt_pk_bf16_f32 v44, v44, v1
	ds_write_b16 v124, v44 offset:53824
	ds_read_u16 v44, v125 offset:37440
	v_fma_f32 v42, v149, v47, v42
	v_fmac_f32_e32 v42, v55, v46
	v_fmac_f32_e32 v43, v148, v47
	v_fmac_f32_e32 v43, v58, v46
	s_waitcnt lgkmcnt(0)
	v_lshlrev_b32_e32 v44, 16, v44
	v_mul_f32_e32 v44, v45, v44
	v_cvt_pk_bf16_f32 v44, v44, v1
	ds_write_b16 v125, v44 offset:53824
	ds_read_u16 v44, v126 offset:37440
	v_fma_f32 v40, v147, v48, v40
	v_fmac_f32_e32 v40, v63, v0
	v_fmac_f32_e32 v41, v146, v48
	v_fmac_f32_e32 v41, v62, v0
	s_waitcnt lgkmcnt(0)
	v_lshlrev_b32_e32 v44, 16, v44
	v_mul_f32_e32 v42, v42, v44
	v_cvt_pk_bf16_f32 v42, v42, v1
	ds_write_b16 v126, v42 offset:53824
	ds_read_u16 v42, v127 offset:37440
	v_fma_f32 v38, v145, v48, v38
	v_fmac_f32_e32 v38, v56, v0
	v_fmac_f32_e32 v39, v144, v48
	v_fmac_f32_e32 v39, v59, v0
	s_waitcnt lgkmcnt(0)
	v_lshlrev_b32_e32 v42, 16, v42
	v_mul_f32_e32 v42, v43, v42
	v_cvt_pk_bf16_f32 v42, v42, v1
	ds_write_b16 v127, v42 offset:53824
	ds_read_u16 v42, v124 offset:37472
	v_fma_f32 v36, v143, v47, v36
	v_fmac_f32_e32 v36, v65, v46
	v_fmac_f32_e32 v37, v142, v47
	v_fmac_f32_e32 v37, v64, v46
	s_waitcnt lgkmcnt(0)
	v_lshlrev_b32_e32 v42, 16, v42
	v_mul_f32_e32 v40, v40, v42
	v_cvt_pk_bf16_f32 v40, v40, v1
	ds_write_b16 v124, v40 offset:53856
	ds_read_u16 v40, v125 offset:37472
	v_fma_f32 v34, v141, v47, v34
	v_fmac_f32_e32 v34, v60, v46
	v_fmac_f32_e32 v35, v140, v47
	v_fmac_f32_e32 v35, v57, v46
	s_waitcnt lgkmcnt(0)
	v_lshlrev_b32_e32 v40, 16, v40
	v_mul_f32_e32 v40, v41, v40
	v_cvt_pk_bf16_f32 v40, v40, v1
	ds_write_b16 v125, v40 offset:53856
	ds_read_u16 v40, v126 offset:37472
	v_fma_f32 v32, v139, v48, v32
	v_fmac_f32_e32 v32, v61, v0
	v_fmac_f32_e32 v33, v138, v48
	v_fmac_f32_e32 v33, v53, v0
	s_waitcnt lgkmcnt(0)
	v_lshlrev_b32_e32 v40, 16, v40
	v_mul_f32_e32 v38, v38, v40
	v_cvt_pk_bf16_f32 v38, v38, v1
	ds_write_b16 v126, v38 offset:53856
	ds_read_u16 v38, v127 offset:37472
	v_fma_f32 v30, v137, v48, v30
	v_fmac_f32_e32 v30, v51, v0
	v_fmac_f32_e32 v31, v136, v48
	v_fmac_f32_e32 v31, v50, v0
	s_waitcnt lgkmcnt(0)
	v_lshlrev_b32_e32 v38, 16, v38
	v_mul_f32_e32 v38, v39, v38
	v_cvt_pk_bf16_f32 v38, v38, v1
	ds_write_b16 v127, v38 offset:53856
	ds_read_u16 v38, v128 offset:37440
	s_lshl_b32 s68, s53, 1
	s_mov_b32 s78, 1
	s_andn2_b64 vcc, exec, s[94:95]
	s_mov_b64 s[26:27], 0
	s_waitcnt lgkmcnt(0)
	v_lshlrev_b32_e32 v38, 16, v38
	v_mul_f32_e32 v36, v36, v38
	v_cvt_pk_bf16_f32 v36, v36, v1
	ds_write_b16 v128, v36 offset:53824
	ds_read_u16 v36, v129 offset:37440
	v_lshl_add_u64 v[38:39], v[20:21], 0, s[68:69]
	v_lshl_add_u64 v[40:41], v[38:39], 0, v[26:27]
	v_lshl_add_u64 v[38:39], v[38:39], 0, v[28:29]
	s_waitcnt lgkmcnt(0)
	v_lshlrev_b32_e32 v36, 16, v36
	v_mul_f32_e32 v36, v37, v36
	v_cvt_pk_bf16_f32 v36, v36, v1
	ds_write_b16 v129, v36 offset:53824
	ds_read_u16 v36, v130 offset:37440
	s_waitcnt lgkmcnt(0)
	v_lshlrev_b32_e32 v36, 16, v36
	v_mul_f32_e32 v34, v34, v36
	v_cvt_pk_bf16_f32 v34, v34, v1
	ds_write_b16 v130, v34 offset:53824
	ds_read_u16 v34, v131 offset:37440
	s_waitcnt lgkmcnt(0)
	v_lshlrev_b32_e32 v34, 16, v34
	v_mul_f32_e32 v34, v35, v34
	v_cvt_pk_bf16_f32 v34, v34, v1
	ds_write_b16 v131, v34 offset:53824
	ds_read_u16 v34, v128 offset:37472
	s_waitcnt lgkmcnt(0)
	v_lshlrev_b32_e32 v34, 16, v34
	v_mul_f32_e32 v32, v32, v34
	v_cvt_pk_bf16_f32 v32, v32, v1
	ds_write_b16 v128, v32 offset:53856
	ds_read_u16 v32, v129 offset:37472
	s_waitcnt lgkmcnt(0)
	v_lshlrev_b32_e32 v32, 16, v32
	v_mul_f32_e32 v32, v33, v32
	v_cvt_pk_bf16_f32 v32, v32, v1
	ds_write_b16 v129, v32 offset:53856
	ds_read_u16 v32, v130 offset:37472
	s_waitcnt lgkmcnt(0)
	v_lshlrev_b32_e32 v32, 16, v32
	v_mul_f32_e32 v30, v30, v32
	v_cvt_pk_bf16_f32 v30, v30, v1
	ds_write_b16 v130, v30 offset:53856
	ds_read_u16 v30, v131 offset:37472
	s_waitcnt lgkmcnt(0)
	v_lshlrev_b32_e32 v0, 16, v30
	v_mul_f32_e32 v0, v31, v0
	v_cvt_pk_bf16_f32 v0, v0, v1
	ds_write_b16 v131, v0 offset:53856
	s_waitcnt lgkmcnt(0)
	s_barrier
	ds_read_b128 v[30:33], v133 offset:53824
	ds_read_b128 v[34:37], v134 offset:53824
	s_waitcnt lgkmcnt(0)
	global_store_dwordx4 v[40:41], v[30:33], off
	global_store_dwordx4 v[38:39], v[34:37], off
	s_cbranch_vccz .LBB0_709
